# v108 + GU GEMM: next-tile decode (52 SALU, branch-free) moved from the serial tile start to the end of the tile's second load segment (hidden under the other half's MFMA block)
# baseline (speedup 1.0000x reference)
; #define PG8_STAGE(bufoff, gbase, voff) do { _Pragma("unroll") for (int _i = 0; _i < 2; ++_i) \
;         __builtin_amdgcn_global_load_lds((const unsigned*)((const char*)(gbase) + (voff)[_i]), (PG8_LAS unsigned*)(lds + (bufoff) + ldsw + _i * 8192), 16, 0, 0); } while (0)
; #define PG8_LDA(dst, b, h) do { _Pragma("unroll") for (int m = 0; m < 4; ++m) _Pragma("unroll") for (int k = 0; k < 2; ++k) dst[m][k] = *(const PG8_LAS bf16x8*)(lds + PG8_SA(b, h) + aoff + m * 2048 + k * 1024); } while (0)
; #define PG8_LDB(dst, b, h) do { _Pragma("unroll") for (int n = 0; n < 2; ++n) _Pragma("unroll") for (int k = 0; k < 2; ++k) dst[n][k] = *(const PG8_LAS bf16x8*)(lds + PG8_SB(b, h) + boff + n * 2048 + k * 1024); } while (0)
; #define PG8_MMA(ai, bj, At, Bt) do { __builtin_amdgcn_s_setprio(1); _Pragma("unroll") for (int m = 0; m < 4; ++m) _Pragma("unroll") for (int n = 0; n < 2; ++n) _Pragma("unroll") for (int k = 0; k < 2; ++k) \
;         acc[ai][bj][m][n] = __builtin_amdgcn_mfma_f32_16x16x32_bf16(Bt[n][k], At[m][k], acc[ai][bj][m][n], 0, 0, 0); __builtin_amdgcn_s_setprio(0); } while (0)
; #define PG8_WAIT_V(n) asm volatile("s_waitcnt vmcnt(" #n ")" ::: "memory")
; #define PG8_WAIT_L(n) asm volatile("s_waitcnt lgkmcnt(" #n ")" ::: "memory")
; #define PG8_BAR __builtin_amdgcn_s_barrier()
; #define PG8_SCHED __builtin_amdgcn_sched_barrier(0)
; template <class Epi, class Sched, bool ALIGN_EPI = false, bool SP2 = false>
; __device__ __forceinline__ void gemm_phase(PG8_LAS unsigned char* lds, const Gemm g, const Sched& S, const Epi& E) {
;     ...
;             const char* a1 = cA + (size_t)(t + 1) * kstep;
;             const char* a2 = last ? nA : cA + (size_t)(t + 2) * kstep; const char* b2 = last ? nB : cB + (size_t)(t + 2) * kstep;
;             const char* a3 = a2 + kstep; const char* b3 = b2 + kstep;
;             if (last && has_next) S.a_ready(nxt);
;             if constexpr (SP2) {
;             PG8_LDB(B0, 0, 0); PG8_LDB(B1, 0, 1); PG8_SCHED; PG8_LDA(At, 0, 0); PG8_STAGE(PG8_SA(1, 1), a1 + hstep, voffA);
;             PG8_WAIT_V(8); PG8_WAIT_L(0); PG8_BAR; PG8_MMA(0, 0, At, B0); PG8_MMA(0, 1, At, B1); PG8_BAR; PG8_SCHED;
.LBB0_402:
	s_add_u32 s8, s8, 0x40080
	s_addc_u32 s9, s9, 0
	s_add_u32 s44, s24, 0x100
	s_addc_u32 s45, s25, 0
	s_mov_b32 s46, -2
	s_add_u32 s24, s8, 0xfffc0080
	s_addc_u32 s25, s9, -1
	s_cmp_eq_u32 s46, 12
	s_cselect_b32 s27, s7, s25
	s_cselect_b32 s26, s17, s24
	s_cselect_b32 s25, s19, s45
	s_cselect_b32 s24, s43, s44
	s_add_i32 s50, 0, 0x14000
	ds_read_b128 v[144:147], v164
	ds_read_b128 v[148:151], v164 offset:1024
	ds_read_b128 v[152:155], v164 offset:2048
	ds_read_b128 v[156:159], v164 offset:3072
	ds_read_b128 v[160:163], v164 offset:16384
	ds_read_b128 v[168:171], v164 offset:17408
	ds_read_b128 v[172:175], v164 offset:18432
	ds_read_b128 v[176:179], v164 offset:19456
	v_lshl_add_u64 v[198:199], s[8:9], 0, v[140:141]
	s_add_i32 m0, s37, 0xc000
	ds_read_b128 v[180:183], v166
	ds_read_b128 v[184:187], v166 offset:1024
	ds_read_b128 v[188:191], v166 offset:2048
	ds_read_b128 v[192:195], v166 offset:3072
	ds_read_b128 v[202:205], v166 offset:4096
	ds_read_b128 v[206:209], v166 offset:5120
	ds_read_b128 v[210:213], v166 offset:6144
	ds_read_b128 v[214:217], v166 offset:7168
	global_load_lds_dwordx4 v[198:199], off
	s_add_i32 m0, s37, 0xe000
	v_lshl_add_u64 v[198:199], s[8:9], 0, v[142:143]
	global_load_lds_dwordx4 v[198:199], off
	s_waitcnt vmcnt(8) lgkmcnt(0)
	s_barrier
	s_setprio 1
	v_mfma_f32_16x16x32_bf16 v[128:131], v[144:147], v[180:183], 0
	v_mfma_f32_16x16x32_bf16 v[120:123], v[152:155], v[180:183], 0
	v_mfma_f32_16x16x32_bf16 v[112:115], v[144:147], v[188:191], 0
	v_mfma_f32_16x16x32_bf16 v[104:107], v[152:155], v[188:191], 0
	v_mfma_f32_16x16x32_bf16 v[96:99], v[144:147], v[202:205], 0
	v_mfma_f32_16x16x32_bf16 v[88:91], v[152:155], v[202:205], 0
	v_mfma_f32_16x16x32_bf16 v[80:83], v[144:147], v[210:213], 0
	v_mfma_f32_16x16x32_bf16 v[72:75], v[152:155], v[210:213], 0
	v_mfma_f32_16x16x32_bf16 v[128:131], v[148:151], v[184:187], v[128:131]
	v_mfma_f32_16x16x32_bf16 v[120:123], v[156:159], v[184:187], v[120:123]
	v_mfma_f32_16x16x32_bf16 v[112:115], v[148:151], v[192:195], v[112:115]
	v_mfma_f32_16x16x32_bf16 v[104:107], v[156:159], v[192:195], v[104:107]
	v_mfma_f32_16x16x32_bf16 v[96:99], v[148:151], v[206:209], v[96:99]
	v_mfma_f32_16x16x32_bf16 v[88:91], v[156:159], v[206:209], v[88:91]
	v_mfma_f32_16x16x32_bf16 v[80:83], v[148:151], v[214:217], v[80:83]
	v_mfma_f32_16x16x32_bf16 v[72:75], v[156:159], v[214:217], v[72:75]
	s_setprio 0
	s_setprio 1
	v_mfma_f32_16x16x32_bf16 v[124:127], v[160:163], v[180:183], 0
	v_mfma_f32_16x16x32_bf16 v[116:119], v[172:175], v[180:183], 0
	v_mfma_f32_16x16x32_bf16 v[108:111], v[160:163], v[188:191], 0
	v_mfma_f32_16x16x32_bf16 v[100:103], v[172:175], v[188:191], 0
	v_mfma_f32_16x16x32_bf16 v[92:95], v[160:163], v[202:205], 0
	v_mfma_f32_16x16x32_bf16 v[84:87], v[172:175], v[202:205], 0
	v_mfma_f32_16x16x32_bf16 v[76:79], v[160:163], v[210:213], 0
	v_mfma_f32_16x16x32_bf16 v[68:71], v[172:175], v[210:213], 0
	v_mfma_f32_16x16x32_bf16 v[124:127], v[168:171], v[184:187], v[124:127]
	v_mfma_f32_16x16x32_bf16 v[116:119], v[176:179], v[184:187], v[116:119]
	v_mfma_f32_16x16x32_bf16 v[108:111], v[168:171], v[192:195], v[108:111]
	v_mfma_f32_16x16x32_bf16 v[100:103], v[176:179], v[192:195], v[100:103]
	v_mfma_f32_16x16x32_bf16 v[92:95], v[168:171], v[206:209], v[92:95]
	v_mfma_f32_16x16x32_bf16 v[84:87], v[176:179], v[206:209], v[84:87]
	v_mfma_f32_16x16x32_bf16 v[76:79], v[168:171], v[214:217], v[76:79]
	v_mfma_f32_16x16x32_bf16 v[68:71], v[176:179], v[214:217], v[68:71]
	s_setprio 0
	s_barrier
; #define PG8_STAGE(bufoff, gbase, voff) do { _Pragma("unroll") for (int _i = 0; _i < 2; ++_i) \
;         __builtin_amdgcn_global_load_lds((const unsigned*)((const char*)(gbase) + (voff)[_i]), (PG8_LAS unsigned*)(lds + (bufoff) + ldsw + _i * 8192), 16, 0, 0); } while (0)
; #define PG8_LDA(dst, b, h) do { _Pragma("unroll") for (int m = 0; m < 4; ++m) _Pragma("unroll") for (int k = 0; k < 2; ++k) dst[m][k] = *(const PG8_LAS bf16x8*)(lds + PG8_SA(b, h) + aoff + m * 2048 + k * 1024); } while (0)
; #define PG8_MMA(ai, bj, At, Bt) do { __builtin_amdgcn_s_setprio(1); _Pragma("unroll") for (int m = 0; m < 4; ++m) _Pragma("unroll") for (int n = 0; n < 2; ++n) _Pragma("unroll") for (int k = 0; k < 2; ++k) \
;         acc[ai][bj][m][n] = __builtin_amdgcn_mfma_f32_16x16x32_bf16(Bt[n][k], At[m][k], acc[ai][bj][m][n], 0, 0, 0); __builtin_amdgcn_s_setprio(0); } while (0)
; #define PG8_WAIT_V(n) asm volatile("s_waitcnt vmcnt(" #n ")" ::: "memory")
; #define PG8_WAIT_L(n) asm volatile("s_waitcnt lgkmcnt(" #n ")" ::: "memory")
; #define PG8_BAR __builtin_amdgcn_s_barrier()
; #define PG8_SCHED __builtin_amdgcn_sched_barrier(0)
;     __host__ __device__ bool next(int i, Unit& u) const {
;         const long L = (long)i * G + c; if (L >= nwg) return false;
;         int wgid = (int)L; { const int q = nwg / NXCD, r = nwg % NXCD, xcd = wgid % NXCD, off = wgid / NXCD; wgid = (xcd < r ? xcd * (q + 1) : r * (q + 1) + (xcd - r) * q) + off; }
;         const int nig = WGM * nN, gid = wgid / nig, fm = gid * WGM, gsz = (nM - fm) < WGM ? (nM - fm) : WGM;
;         u.pm = fm + ((wgid % nig) % gsz); u.pn = (wgid % nig) / gsz; return true;
; template <class Epi, class Sched, bool ALIGN_EPI = false, bool SP2 = false>
; __device__ __forceinline__ void gemm_phase(PG8_LAS unsigned char* lds, const Gemm g, const Sched& S, const Epi& E) {
;     ...
;             PG8_LDA(At, 0, 1); PG8_STAGE(PG8_SB(0, 0), b2, voffB); PG8_STAGE(PG8_SB(0, 1), b2 + hstep, voffB); PG8_STAGE(PG8_SA(0, 0), a2, voffA);
;             PG8_WAIT_V(8); PG8_WAIT_L(0); PG8_BAR; PG8_MMA(1, 0, At, B0); PG8_MMA(1, 1, At, B1); PG8_BAR; PG8_SCHED;
	v_lshl_add_u64 v[198:199], s[24:25], 0, v[134:135]
	s_add_i32 m0, s35, 0x10000
	ds_read_b128 v[180:183], v166 offset:16384
	ds_read_b128 v[184:187], v166 offset:17408
	ds_read_b128 v[188:191], v166 offset:18432
	ds_read_b128 v[192:195], v166 offset:19456
	ds_read_b128 v[202:205], v166 offset:20480
	ds_read_b128 v[206:209], v166 offset:21504
	ds_read_b128 v[210:213], v166 offset:22528
	ds_read_b128 v[214:217], v166 offset:23552
	global_load_lds_dwordx4 v[198:199], off
	s_add_i32 m0, s35, 0x12000
	s_add_u32 s48, s24, 0x40000
	v_lshl_add_u64 v[218:219], s[24:25], 0, v[0:1]
	s_addc_u32 s49, s25, 0
	global_load_lds_dwordx4 v[218:219], off
	v_lshl_add_u64 v[244:245], s[48:49], 0, v[134:135]
	s_add_i32 m0, s35, 0x14000
	v_lshl_add_u64 v[222:223], s[26:27], 0, v[132:133]
	global_load_lds_dwordx4 v[244:245], off
	s_add_i32 m0, s35, 0x16000
	v_lshl_add_u64 v[246:247], s[48:49], 0, v[0:1]
	global_load_lds_dwordx4 v[246:247], off
	v_lshl_add_u64 v[220:221], s[26:27], 0, v[136:137]
	s_add_i32 s72, s72, 1
	s_lshl_b64 s[4:5], s[72:73], 8
	s_add_u32 s20, s4, s28
	s_addc_u32 s21, s5, s36
	s_cmp_lt_u32 s20, 0xb00
	s_cselect_b64 s[4:5], -1, 0
	s_cmp_eq_u32 s21, 0
	s_cselect_b64 vcc, -1, 0
	s_and_b64 s[4:5], s[4:5], vcc
	s_ashr_i32 s7, s20, 31
	s_lshr_b32 s7, s7, 29
	s_add_i32 s7, s20, s7
	s_ashr_i32 s16, s7, 3
	s_and_b32 s7, s7, -8
	s_sub_i32 s7, s20, s7
	s_cmp_lt_i32 s7, 0
	s_cselect_b32 s17, s74, 0x160
	s_mul_i32 s7, s7, s17
	s_add_i32 s7, s7, s16
	s_mul_hi_i32 s16, s7, 0x2e8ba2e9
	s_lshr_b32 s17, s16, 31
	s_ashr_i32 s16, s16, 5
	s_add_i32 s16, s16, s17
	s_lshl_b32 s17, s16, 3
	s_mulk_i32 s16, 0xb0
	s_sub_i32 s7, s7, s16
	s_bfe_u32 s16, s7, 0x3001c
	s_add_i32 s16, s7, s16
	s_sext_i32_i16 s18, s16
	s_and_b32 s16, s16, 0xfff8
	s_sub_i32 s7, s7, s16
	s_sext_i32_i16 s7, s7
	s_add_i32 s16, s17, s7
	s_ashr_i32 s18, s18, 3
	s_ashr_i32 s17, s16, 31
	s_lshl_b64 s[20:21], s[16:17], 19
	s_add_u32 s20, s29, s20
	s_addc_u32 s21, s30, s21
	s_add_u32 s22, s8, 0xfffbff80
	s_addc_u32 s23, s9, -1
	s_and_b64 vcc, s[4:5], exec
	s_cselect_b32 s7, s21, s23
	s_cselect_b32 s17, s20, s22
	s_ashr_i32 s19, s18, 31
	s_lshl_b64 s[22:23], s[18:19], 19
	s_add_u32 s22, s31, s22
	s_addc_u32 s23, s34, s23
	s_add_u32 s100, s44, 0xffffff00
	s_addc_u32 s101, s45, -1
	s_and_b64 vcc, s[4:5], exec
	s_cselect_b32 s19, s23, s101
	s_cselect_b32 s43, s22, s100
	s_waitcnt vmcnt(6) lgkmcnt(0)
	s_barrier
	s_setprio 1
	v_mfma_f32_16x16x32_bf16 v[64:67], v[144:147], v[180:183], 0
	v_mfma_f32_16x16x32_bf16 v[56:59], v[152:155], v[180:183], 0
	v_mfma_f32_16x16x32_bf16 v[48:51], v[144:147], v[188:191], 0
	v_mfma_f32_16x16x32_bf16 v[40:43], v[152:155], v[188:191], 0
	v_mfma_f32_16x16x32_bf16 v[32:35], v[144:147], v[202:205], 0
	v_mfma_f32_16x16x32_bf16 v[24:27], v[152:155], v[202:205], 0
	v_mfma_f32_16x16x32_bf16 v[16:19], v[144:147], v[210:213], 0
	v_mfma_f32_16x16x32_bf16 v[8:11], v[152:155], v[210:213], 0
	v_mfma_f32_16x16x32_bf16 v[64:67], v[148:151], v[184:187], v[64:67]
	v_mfma_f32_16x16x32_bf16 v[56:59], v[156:159], v[184:187], v[56:59]
	v_mfma_f32_16x16x32_bf16 v[48:51], v[148:151], v[192:195], v[48:51]
	v_mfma_f32_16x16x32_bf16 v[40:43], v[156:159], v[192:195], v[40:43]
	v_mfma_f32_16x16x32_bf16 v[32:35], v[148:151], v[206:209], v[32:35]
	v_mfma_f32_16x16x32_bf16 v[24:27], v[156:159], v[206:209], v[24:27]
	v_mfma_f32_16x16x32_bf16 v[16:19], v[148:151], v[214:217], v[16:19]
	v_mfma_f32_16x16x32_bf16 v[8:11], v[156:159], v[214:217], v[8:11]
	s_setprio 0
	s_setprio 1
	v_mfma_f32_16x16x32_bf16 v[60:63], v[160:163], v[180:183], 0
	v_mfma_f32_16x16x32_bf16 v[52:55], v[172:175], v[180:183], 0
	v_mfma_f32_16x16x32_bf16 v[44:47], v[160:163], v[188:191], 0
	v_mfma_f32_16x16x32_bf16 v[36:39], v[172:175], v[188:191], 0
	v_mfma_f32_16x16x32_bf16 v[28:31], v[160:163], v[202:205], 0
	v_mfma_f32_16x16x32_bf16 v[20:23], v[172:175], v[202:205], 0
	v_mfma_f32_16x16x32_bf16 v[12:15], v[160:163], v[210:213], 0
	v_mfma_f32_16x16x32_bf16 v[4:7], v[172:175], v[210:213], 0
	v_mfma_f32_16x16x32_bf16 v[60:63], v[168:171], v[184:187], v[60:63]
	v_mfma_f32_16x16x32_bf16 v[52:55], v[176:179], v[184:187], v[52:55]
	v_mfma_f32_16x16x32_bf16 v[44:47], v[168:171], v[192:195], v[44:47]
	v_mfma_f32_16x16x32_bf16 v[36:39], v[176:179], v[192:195], v[36:39]
	v_mfma_f32_16x16x32_bf16 v[28:31], v[168:171], v[206:209], v[28:31]
	v_mfma_f32_16x16x32_bf16 v[20:23], v[176:179], v[206:209], v[20:23]
	v_mfma_f32_16x16x32_bf16 v[12:15], v[168:171], v[214:217], v[12:15]
	v_mfma_f32_16x16x32_bf16 v[4:7], v[176:179], v[214:217], v[4:7]
	s_setprio 0
	s_barrier
	s_branch .Lkmid_2
